# v18 + both K=1024 gemm_small bodies software-pipelined (3 rotating operand half-sets, 16-24 loads kept in flight)
# baseline (speedup 1.0000x reference)
; #define MFMA16(a, b, c) __builtin_amdgcn_mfma_f32_16x16x32_bf16((a), (b), (c), 0, 0, 0)
; DI int tidx() { int t = threadIdx.x; asm volatile("" : "+v"(t)); return t; }
; DI int bidx() { int b = blockIdx.x; asm volatile("" : "+s"(b)); return b; }
; DI int gdim() { int g = gridDim.x; asm volatile("" : "+s"(g)); return g; }
; DI void gemm_small(const bf16_t* __restrict__ A, const bf16_t* __restrict__ Bt, int K, bf16_t* __restrict__ Yo) {
;     const int tid = tidx(), lane = tid & 63, wave = tid >> 6, fr = lane & 15, g = lane >> 4;
;     for (int t = bidx(); t < 256; t += gdim()) {
;         const int row = MP + (t >> 4) * 32 + (wave >> 2) * 16, col = (t & 15) * 64 + (wave & 3) * 16;
;         const bf16_t* ap = A + (size_t)(row + fr) * K + 8 * g;
;         const bf16_t* bp = Bt + (size_t)(col + fr) * K + 8 * g;
;         f32x4 acc = (f32x4){0.f, 0.f, 0.f, 0.f};
;         for (int k0 = 0; k0 < K; k0 += 256) {
;             uint4 av[8], bv[8];
; #pragma unroll
;             for (int j = 0; j < 8; ++j) { av[j] = *(const uint4*)(ap + k0 + 32 * j); bv[j] = *(const uint4*)(bp + k0 + 32 * j); }
; #pragma unroll
;             for (int j = 0; j < 8; ++j) acc = MFMA16(asbf(av[j]), asbf(bv[j]), acc);
;         }
.LBB0_493:
	s_lshl_b32 s1, s0, 1
	s_andn2_b32 s1, s1, 31
	v_add_u32_e32 v46, s1, v43
	s_lshl_b32 s1, s0, 6
	v_or_b32_e32 v0, v46, v42
	s_and_b32 s1, s1, 0x3c0
	v_ashrrev_i32_e32 v1, 31, v0
	v_or_b32_e32 v47, s1, v44
	v_lshlrev_b64 v[0:1], 11, v[0:1]
	v_lshl_add_u64 v[38:39], v[32:33], 0, v[0:1]
	v_or_b32_e32 v0, v47, v42
	v_lshlrev_b32_e32 v212, 11, v0
	v_lshl_add_u64 v[40:41], v[34:35], 0, v[212:213]
	global_load_dwordx4 v[48:51], v[38:39], off
	global_load_dwordx4 v[52:55], v[38:39], off offset:64
	global_load_dwordx4 v[56:59], v[38:39], off offset:128
	global_load_dwordx4 v[60:63], v[38:39], off offset:192
	global_load_dwordx4 v[64:67], v[40:41], off
	global_load_dwordx4 v[68:71], v[40:41], off offset:64
	global_load_dwordx4 v[72:75], v[40:41], off offset:128
	global_load_dwordx4 v[76:79], v[40:41], off offset:192
	global_load_dwordx4 v[80:83], v[38:39], off offset:256
	global_load_dwordx4 v[84:87], v[38:39], off offset:320
	global_load_dwordx4 v[88:91], v[38:39], off offset:384
	global_load_dwordx4 v[92:95], v[38:39], off offset:448
	global_load_dwordx4 v[96:99], v[40:41], off offset:256
	global_load_dwordx4 v[100:103], v[40:41], off offset:320
	global_load_dwordx4 v[104:107], v[40:41], off offset:384
	global_load_dwordx4 v[108:111], v[40:41], off offset:448
	global_load_dwordx4 v[112:115], v[38:39], off offset:512
	global_load_dwordx4 v[116:119], v[38:39], off offset:576
	global_load_dwordx4 v[120:123], v[38:39], off offset:640
	global_load_dwordx4 v[124:127], v[38:39], off offset:704
	global_load_dwordx4 v[4:7], v[40:41], off offset:512
	global_load_dwordx4 v[8:11], v[40:41], off offset:576
	global_load_dwordx4 v[12:15], v[40:41], off offset:640
	global_load_dwordx4 v[16:19], v[40:41], off offset:704
	s_waitcnt vmcnt(16)
	v_mfma_f32_16x16x32_bf16 v[0:3], v[48:51], v[64:67], 0
	v_mfma_f32_16x16x32_bf16 v[0:3], v[52:55], v[68:71], v[0:3]
	v_mfma_f32_16x16x32_bf16 v[0:3], v[56:59], v[72:75], v[0:3]
	v_mfma_f32_16x16x32_bf16 v[0:3], v[60:63], v[76:79], v[0:3]
	global_load_dwordx4 v[48:51], v[38:39], off offset:768
	global_load_dwordx4 v[52:55], v[38:39], off offset:832
	global_load_dwordx4 v[56:59], v[38:39], off offset:896
	global_load_dwordx4 v[60:63], v[38:39], off offset:960
	global_load_dwordx4 v[64:67], v[40:41], off offset:768
	global_load_dwordx4 v[68:71], v[40:41], off offset:832
	global_load_dwordx4 v[72:75], v[40:41], off offset:896
	global_load_dwordx4 v[76:79], v[40:41], off offset:960
	s_waitcnt vmcnt(16)
	v_mfma_f32_16x16x32_bf16 v[0:3], v[80:83], v[96:99], v[0:3]
	v_mfma_f32_16x16x32_bf16 v[0:3], v[84:87], v[100:103], v[0:3]
	v_mfma_f32_16x16x32_bf16 v[0:3], v[88:91], v[104:107], v[0:3]
	v_mfma_f32_16x16x32_bf16 v[0:3], v[92:95], v[108:111], v[0:3]
	global_load_dwordx4 v[80:83], v[38:39], off offset:1024
	global_load_dwordx4 v[84:87], v[38:39], off offset:1088
	global_load_dwordx4 v[88:91], v[38:39], off offset:1152
	global_load_dwordx4 v[92:95], v[38:39], off offset:1216
	global_load_dwordx4 v[96:99], v[40:41], off offset:1024
	global_load_dwordx4 v[100:103], v[40:41], off offset:1088
	global_load_dwordx4 v[104:107], v[40:41], off offset:1152
	global_load_dwordx4 v[108:111], v[40:41], off offset:1216
	s_waitcnt vmcnt(16)
	v_mfma_f32_16x16x32_bf16 v[0:3], v[112:115], v[4:7], v[0:3]
	v_mfma_f32_16x16x32_bf16 v[0:3], v[116:119], v[8:11], v[0:3]
	v_mfma_f32_16x16x32_bf16 v[0:3], v[120:123], v[12:15], v[0:3]
	v_mfma_f32_16x16x32_bf16 v[0:3], v[124:127], v[16:19], v[0:3]
	global_load_dwordx4 v[112:115], v[38:39], off offset:1280
	global_load_dwordx4 v[116:119], v[38:39], off offset:1344
	global_load_dwordx4 v[120:123], v[38:39], off offset:1408
	global_load_dwordx4 v[124:127], v[38:39], off offset:1472
	global_load_dwordx4 v[4:7], v[40:41], off offset:1280
	global_load_dwordx4 v[8:11], v[40:41], off offset:1344
	global_load_dwordx4 v[12:15], v[40:41], off offset:1408
	global_load_dwordx4 v[16:19], v[40:41], off offset:1472
	s_waitcnt vmcnt(16)
; #define MFMA16(a, b, c) __builtin_amdgcn_mfma_f32_16x16x32_bf16((a), (b), (c), 0, 0, 0)
; DI void gemm_small(const bf16_t* __restrict__ A, const bf16_t* __restrict__ Bt, int K, bf16_t* __restrict__ Yo) {
;     ...
;             for (int j = 0; j < 8; ++j) acc = MFMA16(asbf(av[j]), asbf(bv[j]), acc);
;         }
; #pragma unroll
;         for (int e = 0; e < 4; ++e) Yo[(size_t)(row + 4 * g + e) * 1024 + col + fr] = f2bf(acc[e]);
	v_mfma_f32_16x16x32_bf16 v[0:3], v[48:51], v[64:67], v[0:3]
	v_mfma_f32_16x16x32_bf16 v[0:3], v[52:55], v[68:71], v[0:3]
	v_mfma_f32_16x16x32_bf16 v[0:3], v[56:59], v[72:75], v[0:3]
	v_mfma_f32_16x16x32_bf16 v[0:3], v[60:63], v[76:79], v[0:3]
	global_load_dwordx4 v[48:51], v[38:39], off offset:1536
	global_load_dwordx4 v[52:55], v[38:39], off offset:1600
	global_load_dwordx4 v[56:59], v[38:39], off offset:1664
	global_load_dwordx4 v[60:63], v[38:39], off offset:1728
	global_load_dwordx4 v[64:67], v[40:41], off offset:1536
	global_load_dwordx4 v[68:71], v[40:41], off offset:1600
	global_load_dwordx4 v[72:75], v[40:41], off offset:1664
	global_load_dwordx4 v[76:79], v[40:41], off offset:1728
	s_waitcnt vmcnt(16)
	v_mfma_f32_16x16x32_bf16 v[0:3], v[80:83], v[96:99], v[0:3]
	v_mfma_f32_16x16x32_bf16 v[0:3], v[84:87], v[100:103], v[0:3]
	v_mfma_f32_16x16x32_bf16 v[0:3], v[88:91], v[104:107], v[0:3]
	v_mfma_f32_16x16x32_bf16 v[0:3], v[92:95], v[108:111], v[0:3]
	global_load_dwordx4 v[80:83], v[38:39], off offset:1792
	global_load_dwordx4 v[84:87], v[38:39], off offset:1856
	global_load_dwordx4 v[88:91], v[38:39], off offset:1920
	global_load_dwordx4 v[92:95], v[38:39], off offset:1984
	global_load_dwordx4 v[96:99], v[40:41], off offset:1792
	global_load_dwordx4 v[100:103], v[40:41], off offset:1856
	global_load_dwordx4 v[104:107], v[40:41], off offset:1920
	global_load_dwordx4 v[108:111], v[40:41], off offset:1984
	s_waitcnt vmcnt(16)
	v_mfma_f32_16x16x32_bf16 v[0:3], v[112:115], v[4:7], v[0:3]
	v_mfma_f32_16x16x32_bf16 v[0:3], v[116:119], v[8:11], v[0:3]
	v_mfma_f32_16x16x32_bf16 v[0:3], v[120:123], v[12:15], v[0:3]
	v_mfma_f32_16x16x32_bf16 v[0:3], v[124:127], v[16:19], v[0:3]
	s_waitcnt vmcnt(8)
	v_mfma_f32_16x16x32_bf16 v[0:3], v[48:51], v[64:67], v[0:3]
	v_mfma_f32_16x16x32_bf16 v[0:3], v[52:55], v[68:71], v[0:3]
	v_mfma_f32_16x16x32_bf16 v[0:3], v[56:59], v[72:75], v[0:3]
	v_mfma_f32_16x16x32_bf16 v[0:3], v[60:63], v[76:79], v[0:3]
	s_waitcnt vmcnt(0)
	v_mfma_f32_16x16x32_bf16 v[0:3], v[80:83], v[96:99], v[0:3]
	v_mfma_f32_16x16x32_bf16 v[0:3], v[84:87], v[100:103], v[0:3]
	v_mfma_f32_16x16x32_bf16 v[0:3], v[88:91], v[104:107], v[0:3]
	v_mfma_f32_16x16x32_bf16 v[0:3], v[92:95], v[108:111], v[0:3]
	v_lshlrev_b32_e32 v212, 1, v47
	s_mov_b32 s1, s96
	v_or_b32_e32 v4, v46, v45
	v_ashrrev_i32_e32 v5, 31, v4
	v_lshl_add_u64 v[6:7], v[36:37], 0, v[212:213]
	v_lshlrev_b64 v[8:9], 11, v[4:5]
	v_lshl_add_u64 v[8:9], v[6:7], 0, v[8:9]
	s_nop 7
	v_cvt_pk_bf16_f32 v0, v0, s0
	global_store_short v[8:9], v0, off
	v_or_b32_e32 v0, 1, v4
	v_cvt_pk_bf16_f32 v5, v1, s0
	v_ashrrev_i32_e32 v1, 31, v0
	v_lshlrev_b64 v[0:1], 11, v[0:1]
	v_lshl_add_u64 v[0:1], v[6:7], 0, v[0:1]
	global_store_short v[0:1], v5, off
	v_or_b32_e32 v0, 2, v4
	v_ashrrev_i32_e32 v1, 31, v0
	v_lshlrev_b64 v[0:1], 11, v[0:1]
	v_cvt_pk_bf16_f32 v2, v2, s0
	v_lshl_add_u64 v[0:1], v[6:7], 0, v[0:1]
	global_store_short v[0:1], v2, off
	v_or_b32_e32 v0, 3, v4
	v_ashrrev_i32_e32 v1, 31, v0
	v_lshlrev_b64 v[0:1], 11, v[0:1]
	v_cvt_pk_bf16_f32 v2, v3, s0
	v_lshl_add_u64 v[0:1], v[6:7], 0, v[0:1]
	global_store_short v[0:1], v2, off
	s_add_i32 s0, s1, s0
	s_cmpk_lt_i32 s0, 0x100
	s_cbranch_scc1 .LBB0_493
